# diff-attention K/V tiles streamed by LDS-DMA into a 4-slot LDS ring (3 tiles in flight) instead of 1-deep register staging; plus tile body reschedule; bit-identical
# speedup vs baseline: 1.0103x; 1.0103x over previous
; #define LAS __attribute__((address_space(3)))
; __device__ __forceinline__ unsigned cvtpk(float lo, float hi) { const f32x2_t v = {lo, hi}; const bf16x2_t b = __builtin_convertvector(v, bf16x2_t); return __builtin_bit_cast(unsigned, b); }
; #define SLOAD(S, k0) do { S.vs0 = *(const v4u*)(Vg + (size_t)((k0) + sr) * LDP); S.vs1 = *(const v4u*)(Vg + (size_t)((k0) + 32 + sr) * LDP); \
;         if (MODE) { S.ks0 = *(const v4u*)(Kg + (size_t)(k0) * LDP); } \
;         else { S.ks0 = *(const v4u*)(Kg + (size_t)((k0) + sr) * LDP); S.ks1 = *(const v4u*)(Kg + (size_t)((k0) + 32 + sr) * LDP); } } while (0)
; template <int MODE, bool FIXED>
; __device__ __forceinline__ void attn_unit(LAS unsigned char* lds, unsigned char* ws, const AttnParams& P, int l, int Tp, int sq, int h, int qb, int part, int np, int pslot, int tid, int wave, int lane) {
;     ...
;         const bf16* Vg = PROJ + (size_t)seq0 * LDP + vcol + sc;
;         const bf16* Kg = MODE ? PROJ + (size_t)(seq0 + kr1) * LDP + kcol + mp * 64 + kc1 : PROJ + (size_t)seq0 * LDP + kcol + sc;
;         constexpr int DEPTH = 1;
;         struct Stg { v4u vs0, vs1, ks0, ks1; };
;         Stg sA, sB;
;     ...
;         if (MODE == 1 && tid < 64) {
;             const unsigned one2 = 0x3F803F80u, cw = cvtpk((float)tid, (float)tid);
;             *(LAS v4u*)(K_lds + 8192 + tid * 32) = (v4u){one2, cw, 0u, 0u}; *(LAS v4u*)(K_lds + 8192 + tid * 32 + 16) = (v4u){0u, 0u, 0u, 0u}; }
;         if (jlo < jhi) SLOAD(sA, jlo * 64);
;         if (DEPTH == 2 && jlo + 1 < jhi) SLOAD(sB, (jlo + 1) * 64);
.LBB0_929:
	s_lshl_b32 s60, s26, 7
	v_lshl_add_u64 v[2:3], v[150:151], 0, s[60:61]
	global_load_dwordx4 v[114:117], v[2:3], off
	global_load_dwordx4 v[118:121], v[2:3], off offset:32
	global_load_dwordx4 v[122:125], v[2:3], off offset:64
	global_load_dwordx4 v[126:129], v[2:3], off offset:96
	s_and_saveexec_b64 s[10:11], s[6:7]
	s_cbranch_execz .LBB0_931
	v_add_u32_e32 v106, 0x16000, v218
	ds_write_b128 v106, v[134:137] offset:40960
	ds_write_b128 v106, v[138:141] offset:40976
.LBB0_931:
	s_or_b64 exec, exec, s[10:11]
	s_lshl_b32 s10, s26, 6
	s_lshl_b32 s60, s10, 1
	v_lshl_add_u64 v[186:187], v[174:175], 0, s[60:61]
	s_and_saveexec_b64 s[10:11], s[8:9]
	s_cbranch_execz .LBB0_933
	v_readfirstlane_b32 s100, v168
	v_readfirstlane_b32 s101, v188
	s_lshl_b32 s73, s31, 11
	s_mov_b32 s53, 0
	s_add_i32 s101, s101, -1
	v_and_b32_e32 v113, 63, v0
	v_bfe_u32 v110, v113, 2, 3
	v_and_b32_e32 v111, 3, v110
	v_lshrrev_b32_e32 v110, 2, v110
	v_lshl_or_b32 v110, v110, 3, v111
	s_lshr_b32 s3, s31, 1
	s_lshl_b32 s3, s3, 4
	s_and_b32 s32, s31, 1
	s_lshl_b32 s32, s32, 2
	s_add_i32 s3, s3, s32
	v_add_u32_e32 v110, s3, v110
	v_and_b32_e32 v111, 15, v0
	v_lshlrev_b32_e32 v111, 4, v111
	v_sub_co_u32_e64 v108, s[98:99], v172, v111
	s_nop 1
	v_subbrev_co_u32_e64 v109, s[98:99], 0, v173, s[98:99]
	v_mad_i64_i32 v[102:103], s[98:99], v110, s70, v[108:109]
	v_and_b32_e32 v111, 3, v113
	v_lshlrev_b32_e32 v111, 4, v111
	v_lshrrev_b32_e32 v110, 5, v113
	v_lshl_or_b32 v110, v110, 6, v111
	v_mov_b32_e32 v111, 0
	v_lshl_add_u64 v[102:103], v[102:103], 0, v[110:111]
	v_and_b32_e32 v110, 7, v0
	v_lshlrev_b32_e32 v110, 4, v110
	v_bfe_u32 v112, v0, 4, 3
	v_lshlrev_b32_e32 v112, 4, v112
	v_xor_b32_e32 v112, v110, v112
	v_sub_co_u32_e64 v104, s[98:99], v186, v110
	s_nop 1
	v_subbrev_co_u32_e64 v105, s[98:99], 0, v187, s[98:99]
	v_mov_b32_e32 v113, 0
	v_lshl_add_u64 v[104:105], v[104:105], 0, v[112:113]
	s_mov_b32 s99, 0
	s_min_i32 s3, s100, s101
	s_mul_i32 s98, s3, 0x218000
	s_add_i32 s32, s53, s73
	s_mov_b32 m0, s32
	v_lshl_add_u64 v[106:107], v[102:103], 0, s[98:99]
	v_lshl_add_u64 v[108:109], v[104:105], 0, s[98:99]
	global_load_lds_dwordx4 v[106:107], off
	s_add_i32 m0, s32, 0x380
	s_lshr_b32 s3, s73, 1
	s_add_i32 s3, s3, s53
	global_load_lds_dwordx4 v[106:107], off offset:128
	s_add_i32 m0, s3, 0x10000
	s_add_i32 s100, s100, 1
	s_add_i32 s53, s53, 0x4000
	global_load_lds_dwordx4 v[108:109], off
	s_and_b32 s53, s53, 0xc000
	s_min_i32 s3, s100, s101
	s_mul_i32 s98, s3, 0x218000
	s_add_i32 s32, s53, s73
	s_mov_b32 m0, s32
	v_lshl_add_u64 v[106:107], v[102:103], 0, s[98:99]
	v_lshl_add_u64 v[108:109], v[104:105], 0, s[98:99]
	global_load_lds_dwordx4 v[106:107], off
	s_add_i32 m0, s32, 0x380
	s_lshr_b32 s3, s73, 1
	s_add_i32 s3, s3, s53
	global_load_lds_dwordx4 v[106:107], off offset:128
	s_add_i32 m0, s3, 0x10000
	s_add_i32 s100, s100, 1
	s_add_i32 s53, s53, 0x4000
	global_load_lds_dwordx4 v[108:109], off
	s_and_b32 s53, s53, 0xc000
	s_min_i32 s3, s100, s101
	s_mul_i32 s98, s3, 0x218000
	s_add_i32 s32, s53, s73
	s_mov_b32 m0, s32
	v_lshl_add_u64 v[106:107], v[102:103], 0, s[98:99]
	v_lshl_add_u64 v[108:109], v[104:105], 0, s[98:99]
	global_load_lds_dwordx4 v[106:107], off
	s_add_i32 m0, s32, 0x380
	s_lshr_b32 s3, s73, 1
	s_add_i32 s3, s3, s53
	global_load_lds_dwordx4 v[106:107], off offset:128
	s_add_i32 m0, s3, 0x10000
	s_add_i32 s100, s100, 1
	s_add_i32 s53, s53, 0x4000
	global_load_lds_dwordx4 v[108:109], off
	s_and_b32 s53, s53, 0xc000

.LBB0_937:
	s_add_i32 s10, s60, 0xffffc000
	s_and_b32 s29, s10, 0xc000
	s_add_i32 s14, s29, 0x8000
	v_add_u32_e32 v2, 1, v236
	v_cmp_ge_i32_e32 vcc, v2, v188
	v_add_u32_e32 v237, 64, v235
	v_add_u32_e32 v2, s14, v207
	s_waitcnt vmcnt(6)
	s_waitcnt lgkmcnt(0)
	s_barrier
	v_add_u32_e32 v3, v2, v167
	ds_read_b128 v[70:73], v3 offset:32768
	v_add_u32_e32 v3, v2, v212
	ds_read_b128 v[90:93], v3 offset:32768
	v_add_u32_e32 v3, v2, v214
	ds_read_b128 v[94:97], v3 offset:32768
	v_add_u32_e32 v3, v2, v216
	ds_read_b128 v[98:101], v3 offset:32768
	v_add_u32_e32 v3, s14, v211
	ds_read_b128 v[86:89], v3 offset:32768
	v_add_u32_e32 v3, s14, v213
	ds_read_b128 v[228:231], v3 offset:32768
	v_add_u32_e32 v3, s14, v215
	ds_read_b128 v[240:243], v3 offset:32768
	v_add_u32_e32 v3, s14, v217
	ds_read_b128 v[244:247], v3 offset:32768
	v_add_u32_e32 v3, 63, v235
	v_cmp_le_i32_e64 s[12:13], s27, v3
	v_cmp_gt_i32_e64 s[10:11], s27, v3
	v_cmp_ge_i32_e64 s[14:15], s18, v235
	v_cvt_f32_i32_e32 v2, v235
	s_and_b64 s[12:13], s[12:13], s[14:15]
	s_min_i32 s3, s100, s101
	s_mul_i32 s98, s3, 0x218000
	s_add_i32 s32, s53, s73
	s_mov_b32 m0, s32
	v_lshl_add_u64 v[106:107], v[102:103], 0, s[98:99]
	v_lshl_add_u64 v[108:109], v[104:105], 0, s[98:99]
	global_load_lds_dwordx4 v[106:107], off
	s_add_i32 m0, s32, 0x380
	s_lshr_b32 s3, s73, 1
	s_add_i32 s3, s3, s53
	global_load_lds_dwordx4 v[106:107], off offset:128
	s_add_i32 m0, s3, 0x10000
	s_add_i32 s100, s100, 1
	s_add_i32 s53, s53, 0x4000
	global_load_lds_dwordx4 v[108:109], off
	s_and_b32 s53, s53, 0xc000
	s_waitcnt lgkmcnt(7)
	v_mfma_f32_32x32x16_bf16 v[70:85], v[70:73], v[114:117], 0
	s_waitcnt lgkmcnt(6)
	v_mfma_f32_32x32x16_bf16 v[70:85], v[90:93], v[118:121], v[70:85]
	s_waitcnt lgkmcnt(5)
	v_mfma_f32_32x32x16_bf16 v[70:85], v[94:97], v[122:125], v[70:85]
	s_waitcnt lgkmcnt(4)
	v_mfma_f32_32x32x16_bf16 v[70:85], v[98:101], v[126:129], v[70:85]
	s_waitcnt lgkmcnt(3)
	v_mfma_f32_32x32x16_bf16 v[86:101], v[86:89], v[114:117], 0
	s_waitcnt lgkmcnt(2)
	v_mfma_f32_32x32x16_bf16 v[86:101], v[228:231], v[118:121], v[86:101]
	s_waitcnt lgkmcnt(1)
	v_mfma_f32_32x32x16_bf16 v[86:101], v[240:243], v[122:125], v[86:101]
	s_waitcnt lgkmcnt(0)
	v_mfma_f32_32x32x16_bf16 v[86:101], v[244:247], v[126:129], v[86:101]
	s_and_saveexec_b64 s[14:15], s[12:13]
	s_xor_b64 s[12:13], exec, s[14:15]
	s_cbranch_execz .LBB0_941
	v_sub_f32_e32 v2, v190, v2
	s_mov_b32 s14, -2.0
	v_add_f32_e32 v3, -1.0, v2
	s_mov_b32 s15, 0xc0400000
	v_pk_add_f32 v[196:197], v[2:3], s[14:15] op_sel_hi:[0,1]
	v_pk_add_f32 v[228:229], v[2:3], s[62:63] op_sel_hi:[0,1]
	v_pk_add_f32 v[230:231], v[2:3], s[74:75] op_sel_hi:[0,1]
	v_pk_add_f32 v[238:239], v[2:3], s[82:83] op_sel_hi:[0,1]
	v_pk_add_f32 v[240:241], v[2:3], s[94:95] op_sel_hi:[0,1]
	v_pk_add_f32 v[242:243], v[2:3], s[24:25] op_sel_hi:[0,1]
	v_pk_add_f32 v[244:245], v[2:3], s[56:57] op_sel_hi:[0,1]
	s_mov_b32 s14, 0xc2000000
	v_and_b32_e32 v197, 0x7fffffff, v197
	v_and_b32_e32 v196, 0x7fffffff, v196
	v_and_b32_e32 v229, 0x7fffffff, v229
	v_and_b32_e32 v228, 0x7fffffff, v228
	v_and_b32_e32 v231, 0x7fffffff, v231
	v_and_b32_e32 v230, 0x7fffffff, v230
	v_and_b32_e32 v239, 0x7fffffff, v239
	v_and_b32_e32 v238, 0x7fffffff, v238
	v_and_b32_e32 v241, 0x7fffffff, v241
	v_and_b32_e32 v240, 0x7fffffff, v240
	v_and_b32_e32 v243, 0x7fffffff, v243
	v_and_b32_e32 v242, 0x7fffffff, v242
	v_and_b32_e32 v245, 0x7fffffff, v245
	v_and_b32_e32 v244, 0x7fffffff, v244
	v_mov_b32_e32 v183, v182
	s_mov_b32 s15, 0xc2040000
	v_and_b32_e32 v246, 0x7fffffff, v2
	v_and_b32_e32 v247, 0x7fffffff, v3
	v_pk_fma_f32 v[84:85], v[182:183], v[244:245], v[84:85]
	v_pk_fma_f32 v[82:83], v[182:183], v[242:243], v[82:83]
	v_pk_fma_f32 v[80:81], v[182:183], v[240:241], v[80:81]
	v_pk_fma_f32 v[78:79], v[182:183], v[238:239], v[78:79]
	v_pk_fma_f32 v[76:77], v[182:183], v[230:231], v[76:77]
	v_pk_fma_f32 v[74:75], v[182:183], v[228:229], v[74:75]
	v_pk_fma_f32 v[72:73], v[182:183], v[196:197], v[72:73]
	v_pk_add_f32 v[196:197], v[2:3], s[58:59] op_sel_hi:[0,1]
	v_pk_add_f32 v[228:229], v[2:3], s[0:1] op_sel_hi:[0,1]
	v_pk_add_f32 v[230:231], v[2:3], s[20:21] op_sel_hi:[0,1]
	v_pk_add_f32 v[238:239], v[2:3], s[86:87] op_sel_hi:[0,1]
	v_pk_add_f32 v[240:241], v[2:3], s[78:79] op_sel_hi:[0,1]
	v_pk_add_f32 v[242:243], v[2:3], s[66:67] op_sel_hi:[0,1]
	v_pk_add_f32 v[244:245], v[2:3], s[54:55] op_sel_hi:[0,1]
	v_pk_add_f32 v[2:3], v[2:3], s[14:15] op_sel_hi:[0,1]
	v_and_b32_e32 v3, 0x7fffffff, v3
	v_and_b32_e32 v2, 0x7fffffff, v2
	v_and_b32_e32 v245, 0x7fffffff, v245
	v_and_b32_e32 v244, 0x7fffffff, v244
	v_and_b32_e32 v243, 0x7fffffff, v243
	v_and_b32_e32 v242, 0x7fffffff, v242
	v_and_b32_e32 v241, 0x7fffffff, v241
	v_and_b32_e32 v240, 0x7fffffff, v240
	v_and_b32_e32 v239, 0x7fffffff, v239
	v_and_b32_e32 v238, 0x7fffffff, v238
	v_and_b32_e32 v231, 0x7fffffff, v231
	v_and_b32_e32 v230, 0x7fffffff, v230
	v_and_b32_e32 v229, 0x7fffffff, v229
	v_and_b32_e32 v228, 0x7fffffff, v228
	v_and_b32_e32 v197, 0x7fffffff, v197
	v_and_b32_e32 v196, 0x7fffffff, v196
	v_pk_fma_f32 v[70:71], v[184:185], v[246:247], v[70:71]
	v_pk_fma_f32 v[100:101], v[182:183], v[196:197], v[100:101]
	v_pk_fma_f32 v[98:99], v[182:183], v[228:229], v[98:99]
	v_pk_fma_f32 v[96:97], v[182:183], v[230:231], v[96:97]
	v_pk_fma_f32 v[94:95], v[182:183], v[238:239], v[94:95]
	v_pk_fma_f32 v[92:93], v[182:183], v[240:241], v[92:93]
	v_pk_fma_f32 v[90:91], v[182:183], v[242:243], v[90:91]
	v_pk_fma_f32 v[88:89], v[182:183], v[244:245], v[88:89]
	v_pk_fma_f32 v[86:87], v[184:185], v[2:3], v[86:87]
; #define MFMA32(a, b, c) __builtin_amdgcn_mfma_f32_32x32x16_bf16((a), (b), (c), 0, 0, 0)
; #define SBAR() __builtin_amdgcn_sched_barrier(0)
; template <int D0> __device__ __forceinline__ void pv_one(f32x16& od, int vb, bf16x8 pa0, bf16x8 pa1, bf16x8 pa2, bf16x8 pa3) {
;     const s16x4 l0 = tr_read<v_rd_off(D0, 0, 0)>(vb), h0 = tr_read<v_rd_off(D0, 0, 1)>(vb), l1 = tr_read<v_rd_off(D0, 1, 0)>(vb), h1 = tr_read<v_rd_off(D0, 1, 1)>(vb);
;     const s16x4 l2 = tr_read<v_rd_off(D0, 2, 0)>(vb), h2 = tr_read<v_rd_off(D0, 2, 1)>(vb), l3 = tr_read<v_rd_off(D0, 3, 0)>(vb), h3 = tr_read<v_rd_off(D0, 3, 1)>(vb);
;     asm volatile("s_waitcnt lgkmcnt(0)" ::: "memory"); SBAR();
;     ...
;     od = MFMA32(pa0, PK(l0, h0), od); od = MFMA32(pa1, PK(l1, h1), od); od = MFMA32(pa2, PK(l2, h2), od); od = MFMA32(pa3, PK(l3, h3), od);
;     ...
; }
; __device__ __forceinline__ void pv_d0(f32x16* o, int vb, bf16x8 pa0, bf16x8 pa1, bf16x8 pa2, bf16x8 pa3) {
;     pv_one<0>(o[0], vb, pa0, pa1, pa2, pa3); pv_one<1>(o[1], vb, pa0, pa1, pa2, pa3); pv_one<2>(o[2], vb, pa0, pa1, pa2, pa3); pv_one<3>(o[3], vb, pa0, pa1, pa2, pa3);
; }
; template <bool FIXED>
; __device__ __forceinline__ float softmax_tile(f32x16& p0, f32x16& p1, float& m_reg, float& l_reg, bf16x8& pa0, bf16x8& pa1, bf16x8& pa2, bf16x8& pa3) {
;     float alpha = 1.f;
;     if (!FIXED) {
;         float pmax = p0[0];
; #pragma unroll
;         for (int r = 1; r < 16; ++r) pmax = fmaxf(pmax, p0[r]);
; #pragma unroll
;         for (int r = 0; r < 16; ++r) pmax = fmaxf(pmax, p1[r]);
;         pmax = half_max(pmax);
;         if (!__all(pmax - m_reg <= ATT_THR)) { const float mn = fmaxf(m_reg, pmax); alpha = __builtin_amdgcn_exp2f(m_reg - mn); m_reg = mn; }
;         const float mn = m_reg;
; #pragma unroll
;         for (int r = 0; r < 16; ++r) { p0[r] = __builtin_amdgcn_exp2f(p0[r] - mn); p1[r] = __builtin_amdgcn_exp2f(p1[r] - mn); }
;     } else {
; #pragma unroll
;         for (int r = 0; r < 16; ++r) { p0[r] = __builtin_amdgcn_exp2f(p0[r]); p1[r] = __builtin_amdgcn_exp2f(p1[r]); }
;     }
;     float ps = 0.f;
; #pragma unroll
;     for (int r = 0; r < 16; ++r) ps += p0[r];
; #pragma unroll
;     for (int r = 0; r < 16; ++r) ps += p1[r];
;     ps = half_sum(ps);
;     l_reg = l_reg * alpha + ps;
;     ...
;     PK4(p0, 0, pa0); PK4(p0, 8, pa1); PK4(p1, 0, pa2); PK4(p1, 8, pa3);
.LBB0_941:
	s_andn2_saveexec_b64 s[12:13], s[12:13]
	s_cbranch_execz .LBB0_943
	v_cndmask_b32_e64 v3, -v189, v189, s[10:11]
	v_sub_f32_e32 v2, v191, v2
	v_mul_f32_e64 v2, v2, -v3
	v_cvt_pk_bf16_f32 v5, v2, v3
	v_lshlrev_b32_e32 v196, 16, v5
	v_and_b32_e32 v197, 0xffff0000, v5
	v_pk_add_f32 v[2:3], v[2:3], v[196:197] neg_lo:[0,1] neg_hi:[0,1]
	s_nop 0
	v_cvt_pk_bf16_f32 v2, v2, v3
	v_and_b32_e32 v3, 0xffff, v5
	v_lshl_or_b32 v183, v2, 16, v3
	v_lshrrev_b32_e32 v3, 16, v5
	v_and_or_b32 v2, v2, s28, v3
	v_cndmask_b32_e64 v3, 0, v2, s[4:5]
	v_cndmask_b32_e64 v2, 0, v183, s[4:5]
	v_add_u32_e32 v183, v208, v209
	v_add_u32_e32 v183, 0x16000, v183
	ds_read_b128 v[228:231], v183 offset:40960
	v_mov_b32_e32 v5, v4
	v_add_u32_e32 v183, v208, v210
	v_add_u32_e32 v183, 0x16000, v183
	s_waitcnt lgkmcnt(0)
	v_mfma_f32_32x32x16_bf16 v[70:85], v[228:231], v[2:5], v[70:85]
	ds_read_b128 v[228:231], v183 offset:40960
	s_waitcnt lgkmcnt(0)
	v_mfma_f32_32x32x16_bf16 v[86:101], v[228:231], v[2:5], v[86:101]
.LBB0_943:
	s_or_b64 exec, exec, s[12:13]
	v_add_u32_e32 v5, s29, v200
	ds_read_b64_tr_b16 v[228:229], v5 offset:0
	ds_read_b64_tr_b16 v[230:231], v5 offset:2048
	ds_read_b64_tr_b16 v[240:241], v5 offset:512
	ds_read_b64_tr_b16 v[242:243], v5 offset:2560
	ds_read_b64_tr_b16 v[244:245], v5 offset:1024
	ds_read_b64_tr_b16 v[246:247], v5 offset:3072
	s_nop 1
	v_exp_f32_e32 v70, v70
	v_exp_f32_e32 v71, v71
	v_add_f32_e32 v2, 0, v70
	v_exp_f32_e32 v72, v72
	v_add_f32_e32 v2, v71, v2
	v_exp_f32_e32 v73, v73
	v_add_f32_e32 v2, v72, v2
	v_exp_f32_e32 v74, v74
	v_add_f32_e32 v2, v73, v2
	v_exp_f32_e32 v75, v75
	v_add_f32_e32 v2, v74, v2
	v_exp_f32_e32 v76, v76
	v_add_f32_e32 v2, v75, v2
	v_exp_f32_e32 v77, v77
	v_add_f32_e32 v2, v76, v2
	v_cvt_pk_bf16_f32 v70, v70, v71
	v_add_f32_e32 v2, v77, v2
	v_cvt_pk_bf16_f32 v71, v72, v73
	v_cvt_pk_bf16_f32 v72, v74, v75
	v_cvt_pk_bf16_f32 v73, v76, v77
	ds_read_b64_tr_b16 v[74:75], v5 offset:1536
	ds_read_b64_tr_b16 v[76:77], v5 offset:3584
	v_permlane32_swap_b32_e32 v70, v72
	v_permlane32_swap_b32_e32 v71, v73
	s_waitcnt lgkmcnt(6)
	s_nop 0
	v_mfma_f32_32x32x16_bf16 v[54:69], v[70:73], v[228:231], v[54:69]
	ds_read_b64_tr_b16 v[228:229], v5 offset:4096
	ds_read_b64_tr_b16 v[230:231], v5 offset:6144
	v_exp_f32_e32 v78, v78
	v_exp_f32_e32 v79, v79
	v_add_f32_e32 v2, v78, v2
	v_exp_f32_e32 v80, v80
	v_add_f32_e32 v2, v79, v2
	v_exp_f32_e32 v81, v81
	s_waitcnt lgkmcnt(6)
	v_mfma_f32_32x32x16_bf16 v[38:53], v[70:73], v[240:243], v[38:53]
	ds_read_b64_tr_b16 v[240:241], v5 offset:4608
	ds_read_b64_tr_b16 v[242:243], v5 offset:6656
	v_add_f32_e32 v2, v80, v2
	v_exp_f32_e32 v82, v82
	v_add_f32_e32 v2, v81, v2
	v_exp_f32_e32 v83, v83
	v_add_f32_e32 v2, v82, v2
	v_exp_f32_e32 v84, v84
	s_waitcnt lgkmcnt(6)
	v_mfma_f32_32x32x16_bf16 v[22:37], v[70:73], v[244:247], v[22:37]
	ds_read_b64_tr_b16 v[244:245], v5 offset:5120
	ds_read_b64_tr_b16 v[246:247], v5 offset:7168
	v_add_f32_e32 v2, v83, v2
	v_exp_f32_e32 v85, v85
	v_add_f32_e32 v2, v84, v2
	v_cvt_pk_bf16_f32 v78, v78, v79
	v_add_f32_e32 v2, v85, v2
	s_waitcnt lgkmcnt(6)
	v_mfma_f32_32x32x16_bf16 v[6:21], v[70:73], v[74:77], v[6:21]
	v_cvt_pk_bf16_f32 v79, v80, v81
	v_cvt_pk_bf16_f32 v80, v82, v83
	v_cvt_pk_bf16_f32 v81, v84, v85
	ds_read_b64_tr_b16 v[74:75], v5 offset:5632
	ds_read_b64_tr_b16 v[76:77], v5 offset:7680
	v_permlane32_swap_b32_e32 v78, v80
	v_permlane32_swap_b32_e32 v79, v81
	s_waitcnt lgkmcnt(6)
	s_nop 0
	v_mfma_f32_32x32x16_bf16 v[54:69], v[78:81], v[228:231], v[54:69]
	ds_read_b64_tr_b16 v[228:229], v5 offset:8192
	ds_read_b64_tr_b16 v[230:231], v5 offset:10240
	v_exp_f32_e32 v86, v86
	v_exp_f32_e32 v87, v87
	v_add_f32_e32 v2, v86, v2
	v_exp_f32_e32 v88, v88
	v_add_f32_e32 v2, v87, v2
	v_exp_f32_e32 v89, v89
	s_waitcnt lgkmcnt(6)
	v_mfma_f32_32x32x16_bf16 v[38:53], v[78:81], v[240:243], v[38:53]
	ds_read_b64_tr_b16 v[240:241], v5 offset:8704
	ds_read_b64_tr_b16 v[242:243], v5 offset:10752
	v_add_f32_e32 v2, v88, v2
	v_exp_f32_e32 v90, v90
	v_add_f32_e32 v2, v89, v2
	v_exp_f32_e32 v91, v91
	v_add_f32_e32 v2, v90, v2
	v_exp_f32_e32 v92, v92
	s_waitcnt lgkmcnt(6)
	v_mfma_f32_32x32x16_bf16 v[22:37], v[78:81], v[244:247], v[22:37]
	ds_read_b64_tr_b16 v[244:245], v5 offset:9216
	ds_read_b64_tr_b16 v[246:247], v5 offset:11264
	v_add_f32_e32 v2, v91, v2
	v_exp_f32_e32 v93, v93
	v_add_f32_e32 v2, v92, v2
	v_cvt_pk_bf16_f32 v86, v86, v87
	v_add_f32_e32 v2, v93, v2
	s_waitcnt lgkmcnt(6)
	v_mfma_f32_32x32x16_bf16 v[6:21], v[78:81], v[74:77], v[6:21]
	v_cvt_pk_bf16_f32 v87, v88, v89
	v_cvt_pk_bf16_f32 v88, v90, v91
	v_cvt_pk_bf16_f32 v89, v92, v93
	ds_read_b64_tr_b16 v[74:75], v5 offset:9728
	ds_read_b64_tr_b16 v[76:77], v5 offset:11776
	v_permlane32_swap_b32_e32 v86, v88
	v_permlane32_swap_b32_e32 v87, v89
	s_waitcnt lgkmcnt(6)
	s_nop 0
	v_mfma_f32_32x32x16_bf16 v[54:69], v[86:89], v[228:231], v[54:69]
	ds_read_b64_tr_b16 v[228:229], v5 offset:12288
	ds_read_b64_tr_b16 v[230:231], v5 offset:14336
	v_exp_f32_e32 v94, v94
	v_exp_f32_e32 v95, v95
	v_add_f32_e32 v2, v94, v2
	v_exp_f32_e32 v96, v96
	v_add_f32_e32 v2, v95, v2
	v_exp_f32_e32 v97, v97
	s_waitcnt lgkmcnt(6)
	v_mfma_f32_32x32x16_bf16 v[38:53], v[86:89], v[240:243], v[38:53]
	ds_read_b64_tr_b16 v[240:241], v5 offset:12800
	ds_read_b64_tr_b16 v[242:243], v5 offset:14848
	v_add_f32_e32 v2, v96, v2
	v_exp_f32_e32 v98, v98
	v_add_f32_e32 v2, v97, v2
	v_exp_f32_e32 v99, v99
	v_add_f32_e32 v2, v98, v2
	v_exp_f32_e32 v100, v100
	s_waitcnt lgkmcnt(6)
	v_mfma_f32_32x32x16_bf16 v[22:37], v[86:89], v[244:247], v[22:37]
	ds_read_b64_tr_b16 v[244:245], v5 offset:13312
	ds_read_b64_tr_b16 v[246:247], v5 offset:15360
	v_add_f32_e32 v2, v99, v2
	v_exp_f32_e32 v101, v101
	v_add_f32_e32 v2, v100, v2
	v_cvt_pk_bf16_f32 v94, v94, v95
	v_add_f32_e32 v2, v101, v2
	s_waitcnt lgkmcnt(6)
	v_mfma_f32_32x32x16_bf16 v[6:21], v[86:89], v[74:77], v[6:21]
	v_cvt_pk_bf16_f32 v95, v96, v97
	v_cvt_pk_bf16_f32 v96, v98, v99
	v_cvt_pk_bf16_f32 v97, v100, v101
	ds_read_b64_tr_b16 v[74:75], v5 offset:13824
	ds_read_b64_tr_b16 v[76:77], v5 offset:15872
	v_permlane32_swap_b32_e32 v94, v96
	v_permlane32_swap_b32_e32 v95, v97
	v_mov_b32_e32 v3, v2
	s_waitcnt lgkmcnt(6)
	s_nop 0
	v_mfma_f32_32x32x16_bf16 v[54:69], v[94:97], v[228:231], v[54:69]
	v_add_u32_e32 v238, 2, v236
	s_waitcnt lgkmcnt(4)
	v_mfma_f32_32x32x16_bf16 v[38:53], v[94:97], v[240:243], v[38:53]
	v_permlane32_swap_b32_e32 v2, v3
	s_waitcnt lgkmcnt(2)
	v_mfma_f32_32x32x16_bf16 v[22:37], v[94:97], v[244:247], v[22:37]
	s_waitcnt lgkmcnt(0)
	v_mfma_f32_32x32x16_bf16 v[6:21], v[94:97], v[74:77], v[6:21]
	s_and_saveexec_b64 s[10:11], vcc
	s_xor_b64 s[10:11], exec, s[10:11]
	v_add_u32_e32 v236, 2, v236
	s_or_saveexec_b64 s[14:15], s[10:11]
	v_add_f32_e32 v2, v2, v3
	v_add_f32_e32 v219, v219, v2
	s_xor_b64 exec, exec, s[14:15]
	s_cbranch_execz .LBB0_936
	s_and_b32 s29, s60, 0xc000
	s_add_i32 s12, s29, 0x8000
	v_add_u32_e32 v2, s12, v207
	s_waitcnt vmcnt(6)
	s_waitcnt lgkmcnt(0)
	s_barrier
	v_add_u32_e32 v3, v2, v167
	ds_read_b128 v[70:73], v3 offset:32768
	v_add_u32_e32 v3, v2, v212
	ds_read_b128 v[90:93], v3 offset:32768
	v_add_u32_e32 v3, v2, v214
	ds_read_b128 v[94:97], v3 offset:32768
	v_add_u32_e32 v3, v2, v216
	ds_read_b128 v[98:101], v3 offset:32768
	v_add_u32_e32 v3, s12, v211
	ds_read_b128 v[86:89], v3 offset:32768
	v_add_u32_e32 v3, s12, v213
	ds_read_b128 v[228:231], v3 offset:32768
	v_add_u32_e32 v3, s12, v215
	ds_read_b128 v[240:243], v3 offset:32768
	v_add_u32_e32 v3, s12, v217
	ds_read_b128 v[244:247], v3 offset:32768
	v_add_u32_e32 v3, 0x7f, v235
	v_cmp_le_i32_e64 s[10:11], s27, v3
	v_cmp_gt_i32_e32 vcc, s27, v3
	v_cmp_ge_i32_e64 s[12:13], s18, v237
	v_cvt_f32_i32_e32 v2, v237
	s_and_b64 s[10:11], s[10:11], s[12:13]
	s_min_i32 s3, s100, s101
	s_mul_i32 s98, s3, 0x218000
	s_add_i32 s32, s53, s73
	s_mov_b32 m0, s32
	v_lshl_add_u64 v[106:107], v[102:103], 0, s[98:99]
	v_lshl_add_u64 v[108:109], v[104:105], 0, s[98:99]
	global_load_lds_dwordx4 v[106:107], off
	s_add_i32 m0, s32, 0x380
	s_lshr_b32 s3, s73, 1
	s_add_i32 s3, s3, s53
	global_load_lds_dwordx4 v[106:107], off offset:128
	s_add_i32 m0, s3, 0x10000
	s_add_i32 s100, s100, 1
	s_add_i32 s53, s53, 0x4000
	global_load_lds_dwordx4 v[108:109], off
	s_and_b32 s53, s53, 0xc000
	s_waitcnt lgkmcnt(7)
	v_mfma_f32_32x32x16_bf16 v[70:85], v[70:73], v[114:117], 0
	s_waitcnt lgkmcnt(6)
	v_mfma_f32_32x32x16_bf16 v[70:85], v[90:93], v[118:121], v[70:85]
	s_waitcnt lgkmcnt(5)
	v_mfma_f32_32x32x16_bf16 v[70:85], v[94:97], v[122:125], v[70:85]
	s_waitcnt lgkmcnt(4)
	v_mfma_f32_32x32x16_bf16 v[70:85], v[98:101], v[126:129], v[70:85]
	s_waitcnt lgkmcnt(3)
	v_mfma_f32_32x32x16_bf16 v[86:101], v[86:89], v[114:117], 0
	s_waitcnt lgkmcnt(2)
	v_mfma_f32_32x32x16_bf16 v[86:101], v[228:231], v[118:121], v[86:101]
	s_waitcnt lgkmcnt(1)
	v_mfma_f32_32x32x16_bf16 v[86:101], v[240:243], v[122:125], v[86:101]
	s_waitcnt lgkmcnt(0)
	v_mfma_f32_32x32x16_bf16 v[86:101], v[244:247], v[126:129], v[86:101]
	s_and_saveexec_b64 s[12:13], s[10:11]
	s_xor_b64 s[10:11], exec, s[12:13]
	s_cbranch_execz .LBB0_950
	v_sub_f32_e32 v2, v190, v2
	s_mov_b32 s12, -2.0
	v_add_f32_e32 v3, -1.0, v2
	s_mov_b32 s13, 0xc0400000
	v_pk_add_f32 v[196:197], v[2:3], s[12:13] op_sel_hi:[0,1]
	v_pk_add_f32 v[228:229], v[2:3], s[62:63] op_sel_hi:[0,1]
	v_pk_add_f32 v[230:231], v[2:3], s[74:75] op_sel_hi:[0,1]
	v_pk_add_f32 v[236:237], v[2:3], s[82:83] op_sel_hi:[0,1]
	v_pk_add_f32 v[240:241], v[2:3], s[94:95] op_sel_hi:[0,1]
	v_pk_add_f32 v[242:243], v[2:3], s[24:25] op_sel_hi:[0,1]
	v_pk_add_f32 v[244:245], v[2:3], s[56:57] op_sel_hi:[0,1]
	s_mov_b32 s12, 0xc2000000
	v_and_b32_e32 v197, 0x7fffffff, v197
	v_and_b32_e32 v196, 0x7fffffff, v196
	v_and_b32_e32 v229, 0x7fffffff, v229
	v_and_b32_e32 v228, 0x7fffffff, v228
	v_and_b32_e32 v231, 0x7fffffff, v231
	v_and_b32_e32 v230, 0x7fffffff, v230
	v_and_b32_e32 v237, 0x7fffffff, v237
	v_and_b32_e32 v236, 0x7fffffff, v236
	v_and_b32_e32 v241, 0x7fffffff, v241
	v_and_b32_e32 v240, 0x7fffffff, v240
	v_and_b32_e32 v243, 0x7fffffff, v243
	v_and_b32_e32 v242, 0x7fffffff, v242
	v_and_b32_e32 v245, 0x7fffffff, v245
	v_and_b32_e32 v244, 0x7fffffff, v244
	v_mov_b32_e32 v183, v182
	s_mov_b32 s13, 0xc2040000
	v_and_b32_e32 v246, 0x7fffffff, v2
	v_and_b32_e32 v247, 0x7fffffff, v3
	v_pk_fma_f32 v[84:85], v[182:183], v[244:245], v[84:85]
	v_pk_fma_f32 v[82:83], v[182:183], v[242:243], v[82:83]
	v_pk_fma_f32 v[80:81], v[182:183], v[240:241], v[80:81]
	v_pk_fma_f32 v[78:79], v[182:183], v[236:237], v[78:79]
	v_pk_fma_f32 v[76:77], v[182:183], v[230:231], v[76:77]
	v_pk_fma_f32 v[74:75], v[182:183], v[228:229], v[74:75]
	v_pk_fma_f32 v[72:73], v[182:183], v[196:197], v[72:73]
	v_pk_add_f32 v[196:197], v[2:3], s[58:59] op_sel_hi:[0,1]
	v_pk_add_f32 v[228:229], v[2:3], s[0:1] op_sel_hi:[0,1]
	v_pk_add_f32 v[230:231], v[2:3], s[20:21] op_sel_hi:[0,1]
	v_pk_add_f32 v[236:237], v[2:3], s[86:87] op_sel_hi:[0,1]
	v_pk_add_f32 v[240:241], v[2:3], s[78:79] op_sel_hi:[0,1]
	v_pk_add_f32 v[242:243], v[2:3], s[66:67] op_sel_hi:[0,1]
	v_pk_add_f32 v[244:245], v[2:3], s[54:55] op_sel_hi:[0,1]
	v_pk_add_f32 v[2:3], v[2:3], s[12:13] op_sel_hi:[0,1]
	v_and_b32_e32 v3, 0x7fffffff, v3
	v_and_b32_e32 v2, 0x7fffffff, v2
	v_and_b32_e32 v245, 0x7fffffff, v245
	v_and_b32_e32 v244, 0x7fffffff, v244
	v_and_b32_e32 v243, 0x7fffffff, v243
	v_and_b32_e32 v242, 0x7fffffff, v242
	v_and_b32_e32 v241, 0x7fffffff, v241
	v_and_b32_e32 v240, 0x7fffffff, v240
	v_and_b32_e32 v237, 0x7fffffff, v237
	v_and_b32_e32 v236, 0x7fffffff, v236
	v_and_b32_e32 v231, 0x7fffffff, v231
	v_and_b32_e32 v230, 0x7fffffff, v230
	v_and_b32_e32 v229, 0x7fffffff, v229
	v_and_b32_e32 v228, 0x7fffffff, v228
	v_and_b32_e32 v197, 0x7fffffff, v197
	v_and_b32_e32 v196, 0x7fffffff, v196
	v_pk_fma_f32 v[70:71], v[184:185], v[246:247], v[70:71]
	v_pk_fma_f32 v[100:101], v[182:183], v[196:197], v[100:101]
	v_pk_fma_f32 v[98:99], v[182:183], v[228:229], v[98:99]
	v_pk_fma_f32 v[96:97], v[182:183], v[230:231], v[96:97]
	v_pk_fma_f32 v[94:95], v[182:183], v[236:237], v[94:95]
	v_pk_fma_f32 v[92:93], v[182:183], v[240:241], v[92:93]
	v_pk_fma_f32 v[90:91], v[182:183], v[242:243], v[90:91]
	v_pk_fma_f32 v[88:89], v[182:183], v[244:245], v[88:89]
	v_pk_fma_f32 v[86:87], v[184:185], v[2:3], v[86:87]
.LBB0_950:
	s_andn2_saveexec_b64 s[10:11], s[10:11]
	s_cbranch_execz .LBB0_935
	v_cndmask_b32_e64 v3, -v189, v189, vcc
	v_sub_f32_e32 v2, v191, v2
	v_mul_f32_e64 v2, v2, -v3
	v_cvt_pk_bf16_f32 v5, v2, v3
	v_lshlrev_b32_e32 v196, 16, v5
	v_and_b32_e32 v197, 0xffff0000, v5
	v_pk_add_f32 v[2:3], v[2:3], v[196:197] neg_lo:[0,1] neg_hi:[0,1]
	s_nop 0
	v_cvt_pk_bf16_f32 v2, v2, v3
	v_and_b32_e32 v3, 0xffff, v5
	v_lshl_or_b32 v183, v2, 16, v3
	v_lshrrev_b32_e32 v3, 16, v5
	v_and_or_b32 v2, v2, s28, v3
	v_cndmask_b32_e64 v3, 0, v2, s[4:5]
	v_cndmask_b32_e64 v2, 0, v183, s[4:5]
	v_add_u32_e32 v183, v208, v209
	v_add_u32_e32 v183, 0x16000, v183
	ds_read_b128 v[228:231], v183 offset:40960
	v_mov_b32_e32 v5, v4
	v_add_u32_e32 v183, v208, v210
	v_add_u32_e32 v183, 0x16000, v183
	s_waitcnt lgkmcnt(0)
	v_mfma_f32_32x32x16_bf16 v[70:85], v[228:231], v[2:5], v[70:85]
	ds_read_b128 v[228:231], v183 offset:40960
	s_waitcnt lgkmcnt(0)
	v_mfma_f32_32x32x16_bf16 v[86:101], v[228:231], v[2:5], v[86:101]
	s_branch .LBB0_935

; template <int MODE, bool FIXED>
; __device__ __forceinline__ void attn_unit(LAS unsigned char* lds, unsigned char* ws, const AttnParams& P, int l, int Tp, int sq, int h, int qb, int part, int np, int pslot, int tid, int wave, int lane) {
;     ...
;         asm volatile("s_waitcnt lgkmcnt(0)" ::: "memory"); __builtin_amdgcn_s_barrier(); asm volatile("" ::: "memory");
;         if (MODE == 1 && pslot >= 0) {
;             float* po = (float*)(ws + WS_PART) + ((size_t)(pslot * 2 + mp) * 256 + wave * 32 + 4 * hi) * 128 + r32;
; #pragma unroll
;             for (int g = 0; g < 4; ++g) { float* pg = po + g * 8 * 128; asm volatile("" : "+v"(pg));
; #pragma unroll
;                 for (int e = 0; e < 4; ++e)
; #pragma unroll
;                     for (int d = 0; d < 4; ++d) pg[e * 128 + d * 32] = o[d][4 * g + e]; }
;             if (hi == 0) ((float*)(ws + WS_PARTL))[(pslot * 2 + mp) * 256 + wave * 32 + r32] = l_reg;
;         } else
;         if (MODE == 1 && mp == 0) {
.LBB0_953:
	s_or_b64 exec, exec, s[88:89]
	s_waitcnt vmcnt(0)
	s_waitcnt lgkmcnt(0)
	s_barrier
	s_xor_b64 s[10:11], s[84:85], -1
	s_and_b64 vcc, exec, s[80:81]
	s_cbranch_vccz .LBB0_957
	s_mov_b64 s[12:13], 0
	s_and_b64 vcc, exec, s[84:85]
	s_mov_b64 s[14:15], 0
	s_cbranch_vccnz .LBB0_958
	s_and_b64 vcc, exec, s[12:13]
	s_cbranch_vccnz .LBB0_961

; __global__ void __launch_bounds__(NTHREADS, 2) fwd_kernel(Args args) {
	.amdhsa_kernel _Z10fwd_kernel4Args
		.amdhsa_group_segment_fixed_size 0
		.amdhsa_private_segment_fixed_size 0
		.amdhsa_kernarg_size 416
		.amdhsa_user_sgpr_count 2
		.amdhsa_user_sgpr_dispatch_ptr 0
		.amdhsa_user_sgpr_queue_ptr 0
		.amdhsa_user_sgpr_kernarg_segment_ptr 1
		.amdhsa_user_sgpr_dispatch_id 0
		.amdhsa_user_sgpr_kernarg_preload_length 0
		.amdhsa_user_sgpr_kernarg_preload_offset 0
		.amdhsa_user_sgpr_private_segment_size 0
		.amdhsa_uses_dynamic_stack 0
		.amdhsa_enable_private_segment 0
		.amdhsa_system_sgpr_workgroup_id_x 1
		.amdhsa_system_sgpr_workgroup_id_y 0
		.amdhsa_system_sgpr_workgroup_id_z 0
		.amdhsa_system_sgpr_workgroup_info 0
		.amdhsa_system_vgpr_workitem_id 0
		.amdhsa_next_free_vgpr 256
		.amdhsa_next_free_sgpr 102
		.amdhsa_accum_offset 256
		.amdhsa_reserve_vcc 1
		.amdhsa_float_round_mode_32 0
		.amdhsa_float_round_mode_16_64 0
		.amdhsa_float_denorm_mode_32 3
		.amdhsa_float_denorm_mode_16_64 3
		.amdhsa_dx10_clamp 1
		.amdhsa_ieee_mode 1
		.amdhsa_fp16_overflow 0
		.amdhsa_tg_split 0
		.amdhsa_exception_fp_ieee_invalid_op 0
		.amdhsa_exception_fp_denorm_src 0
		.amdhsa_exception_fp_ieee_div_zero 0
		.amdhsa_exception_fp_ieee_overflow 0
		.amdhsa_exception_fp_ieee_underflow 0
		.amdhsa_exception_fp_ieee_inexact 0
		.amdhsa_exception_int_div_zero 0
	.end_amdhsa_kernel

; __global__ void __launch_bounds__(NTHREADS, 2) fwd_kernel(Args args) {
amdhsa.kernels:
  - .agpr_count:     0
    .args:
      - .offset:         0
        .size:           160
        .value_kind:     by_value
      - .offset:         160
        .size:           4
        .value_kind:     hidden_block_count_x
      - .offset:         164
        .size:           4
        .value_kind:     hidden_block_count_y
      - .offset:         168
        .size:           4
        .value_kind:     hidden_block_count_z
      - .offset:         172
        .size:           2
        .value_kind:     hidden_group_size_x
      - .offset:         174
        .size:           2
        .value_kind:     hidden_group_size_y
      - .offset:         176
        .size:           2
        .value_kind:     hidden_group_size_z
      - .offset:         178
        .size:           2
        .value_kind:     hidden_remainder_x
      - .offset:         180
        .size:           2
        .value_kind:     hidden_remainder_y
      - .offset:         182
        .size:           2
        .value_kind:     hidden_remainder_z
      - .offset:         200
        .size:           8
        .value_kind:     hidden_global_offset_x
      - .offset:         208
        .size:           8
        .value_kind:     hidden_global_offset_y
      - .offset:         216
        .size:           8
        .value_kind:     hidden_global_offset_z
      - .offset:         224
        .size:           2
        .value_kind:     hidden_grid_dims
      - .offset:         280
        .size:           4
        .value_kind:     hidden_dynamic_lds_size
    .group_segment_fixed_size: 0
    .kernarg_segment_align: 8
    .kernarg_segment_size: 416
    .language:       OpenCL C
    .language_version:
      - 2
      - 0
    .max_flat_workgroup_size: 512
    .name:           _Z10fwd_kernel4Args
    .private_segment_fixed_size: 0
    .sgpr_count:     108
    .sgpr_spill_count: 372
    .symbol:         _Z10fwd_kernel4Args.kd
    .uniform_work_group_size: 1
    .uses_dynamic_stack: false
    .vgpr_count:     256
    .vgpr_spill_count: 0
    .wavefront_size: 64
